# P2 epilogue scale loads hoisted to one round trip; P1 norm loop: parameter loads issued before next-row prefetch with a counted wait
# speedup vs baseline: 1.0845x; 1.0167x over previous
.LBB0_209:
	s_waitcnt vmcnt(4)
	s_or_b64 exec, exec, s[16:17]
	s_and_b64 s[8:9], exec, s[8:9]
	s_or_b64 s[14:15], s[8:9], s[14:15]
	v_lshl_add_u64 v[44:45], v[44:45], 0, s[2:3]
	v_lshl_add_u64 v[46:47], v[46:47], 0, s[4:5]
	v_lshl_add_u64 v[48:49], v[48:49], 0, s[12:13]
	v_mov_b32_e32 v32, v65
	v_mov_b32_e32 v56, v19
	v_mov_b32_e32 v57, v15
	v_mov_b32_e32 v2, v18
	v_mov_b32_e32 v3, v14
	v_mov_b32_e32 v58, v17
	v_mov_b32_e32 v59, v13
	v_mov_b32_e32 v0, v16
	v_mov_b32_e32 v1, v12
	v_mov_b32_e32 v34, v11
	v_mov_b32_e32 v35, v7
	v_mov_b32_e32 v22, v10
	v_mov_b32_e32 v23, v6
	v_mov_b32_e32 v36, v9
	v_mov_b32_e32 v37, v5
	v_mov_b32_e32 v20, v8
	v_mov_b32_e32 v21, v4
	s_andn2_b64 exec, exec, s[14:15]
	s_cbranch_execz .LBB0_214
.LBB0_210:
	v_add_u32_e32 v65, s30, v32
	s_movk_i32 s8, 0x7fff
	v_cmp_gt_i32_e32 vcc, s19, v65
	v_cmp_lt_i32_e64 s[8:9], s8, v65
	v_ashrrev_i32_e32 v24, 11, v32
	v_mul_i32_i24_e32 v24, 0x1800, v24
	s_mov_b64 s[10:11], 0x1000
	v_ashrrev_i32_e32 v25, 31, v24
	v_lshl_add_u64 v[24:25], v[24:25], 2, s[86:87]
	v_lshl_add_u64 v[32:33], v[24:25], 0, s[10:11]
	v_lshl_add_u64 v[60:61], v[24:25], 0, v[40:41]
	v_lshl_add_u64 v[26:27], v[32:33], 0, v[40:41]
	v_lshl_add_u64 v[28:29], v[32:33], 0, v[50:51]
	v_lshl_add_u64 v[30:31], v[32:33], 0, v[52:53]
	v_lshl_add_u64 v[32:33], v[32:33], 0, v[54:55]
	global_load_dwordx4 v[76:79], v[42:43], off
	global_load_dwordx4 v[80:83], v[42:43], off offset:1024
	global_load_dwordx4 v[84:87], v[42:43], off offset:2048
	global_load_dwordx4 v[88:91], v[42:43], off offset:3072
	global_load_dwordx4 v[92:95], v[26:27], off
	global_load_dwordx4 v[96:99], v[28:29], off
	global_load_dwordx4 v[100:103], v[30:31], off
	global_load_dwordx4 v[104:107], v[32:33], off
	global_load_dwordx4 v[108:111], v[60:61], off
	global_load_dwordx4 v[112:115], v[60:61], off offset:1024
	global_load_dwordx4 v[116:119], v[60:61], off offset:2048
	global_load_dwordx4 v[120:123], v[60:61], off offset:3072
	s_sub_u32 s24, 0, s12
	s_subb_u32 s25, 0, s13
	v_lshl_add_u64 v[124:125], v[48:49], 0, s[24:25]
	v_cndmask_b32_e32 v126, v124, v48, vcc
	v_cndmask_b32_e32 v127, v125, v49, vcc
	global_load_dwordx4 v[4:7], v[126:127], off
	global_load_dwordx4 v[8:11], v[126:127], off offset:1024
	global_load_dwordx4 v[12:15], v[126:127], off offset:2048
	global_load_dwordx4 v[16:19], v[126:127], off offset:3072
	v_pk_mul_f32 v[24:25], v[20:21], v[20:21]
	v_pk_mul_f32 v[26:27], v[0:1], v[0:1]
	v_pk_fma_f32 v[24:25], v[36:37], v[36:37], v[24:25]
	v_pk_fma_f32 v[26:27], v[58:59], v[58:59], v[26:27]
	v_pk_fma_f32 v[24:25], v[22:23], v[22:23], v[24:25]
	v_pk_fma_f32 v[26:27], v[2:3], v[2:3], v[26:27]
	v_pk_fma_f32 v[24:25], v[34:35], v[34:35], v[24:25]
	v_pk_fma_f32 v[26:27], v[56:57], v[56:57], v[26:27]
	v_add_f32_e32 v24, v24, v25
	v_add_f32_e32 v24, v27, v24
	v_add_f32_e32 v24, v26, v24
	s_mov_b32 s10, 0x800000
	v_add_f32_dpp v24, v24, v24 row_ror:8 row_mask:0xf bank_mask:0xf bound_ctrl:1
	s_nop 1
	v_add_f32_dpp v24, v24, v24 row_ror:4 row_mask:0xf bank_mask:0xf bound_ctrl:1
	s_nop 1
	v_add_f32_dpp v24, v24, v24 row_ror:2 row_mask:0xf bank_mask:0xf bound_ctrl:1
	s_nop 1
	v_add_f32_dpp v24, v24, v24 row_ror:1 row_mask:0xf bank_mask:0xf bound_ctrl:1
	ds_bpermute_b32 v25, v62, v24
	s_waitcnt lgkmcnt(0)
	v_add_f32_e32 v24, v24, v25
	ds_bpermute_b32 v25, v63, v24
	s_waitcnt lgkmcnt(0)
	v_add_f32_e32 v24, v24, v25
	v_fmamk_f32 v24, v24, 0x3a800000, v64
	v_cmp_gt_f32_e32 vcc, s10, v24
	v_mul_f32_e32 v25, 0x4b800000, v24
	v_cndmask_b32_e32 v24, v24, v25, vcc
	v_rsq_f32_e32 v24, v24
	s_nop 0
	v_mul_f32_e32 v25, 0x45800000, v24
	v_cndmask_b32_e32 v66, v24, v25, vcc
	s_waitcnt vmcnt(4)
	v_mul_f32_e32 v142, v21, v66
	v_add_f32_e32 v143, 1.0, v92
	v_mul_f32_e32 v142, v76, v142
	v_fma_f32 v24, v143, v142, v108
	v_mul_f32_e32 v142, v37, v66
	v_add_f32_e32 v143, 1.0, v93
	v_mul_f32_e32 v142, v77, v142
	v_fma_f32 v25, v143, v142, v109
	v_mul_f32_e32 v142, v23, v66
	v_add_f32_e32 v143, 1.0, v94
	v_mul_f32_e32 v142, v78, v142
	v_fma_f32 v26, v143, v142, v110
	v_mul_f32_e32 v142, v35, v66
	v_add_f32_e32 v143, 1.0, v95
	v_mul_f32_e32 v142, v79, v142
	v_fma_f32 v27, v143, v142, v111
	v_mul_f32_e32 v142, v20, v66
	v_add_f32_e32 v143, 1.0, v96
	v_mul_f32_e32 v142, v80, v142
	v_fma_f32 v28, v143, v142, v112
	v_mul_f32_e32 v142, v36, v66
	v_add_f32_e32 v143, 1.0, v97
	v_mul_f32_e32 v142, v81, v142
	v_fma_f32 v67, v143, v142, v113
	v_mul_f32_e32 v142, v22, v66
	v_add_f32_e32 v143, 1.0, v98
	v_mul_f32_e32 v142, v82, v142
	v_fma_f32 v29, v143, v142, v114
	v_mul_f32_e32 v142, v34, v66
	v_add_f32_e32 v143, 1.0, v99
	v_mul_f32_e32 v142, v83, v142
	v_fma_f32 v31, v143, v142, v115
	v_mul_f32_e32 v142, v1, v66
	v_add_f32_e32 v143, 1.0, v100
	v_mul_f32_e32 v142, v84, v142
	v_fma_f32 v1, v143, v142, v116
	v_mul_f32_e32 v142, v59, v66
	v_add_f32_e32 v143, 1.0, v101
	v_mul_f32_e32 v142, v85, v142
	v_fma_f32 v59, v143, v142, v117
	v_mul_f32_e32 v142, v3, v66
	v_add_f32_e32 v143, 1.0, v102
	v_mul_f32_e32 v142, v86, v142
	v_fma_f32 v3, v143, v142, v118
	v_mul_f32_e32 v142, v57, v66
	v_add_f32_e32 v143, 1.0, v103
	v_mul_f32_e32 v142, v87, v142
	v_fma_f32 v23, v143, v142, v119
	v_mul_f32_e32 v142, v0, v66
	v_add_f32_e32 v143, 1.0, v104
	v_mul_f32_e32 v142, v88, v142
	v_fma_f32 v20, v143, v142, v120
	v_mul_f32_e32 v142, v58, v66
	v_add_f32_e32 v143, 1.0, v105
	v_mul_f32_e32 v142, v89, v142
	v_fma_f32 v21, v143, v142, v121
	v_mul_f32_e32 v142, v2, v66
	v_add_f32_e32 v143, 1.0, v106
	v_mul_f32_e32 v142, v90, v142
	v_fma_f32 v2, v143, v142, v122
	v_mul_f32_e32 v142, v56, v66
	v_add_f32_e32 v143, 1.0, v107
	v_mul_f32_e32 v142, v91, v142
	v_fma_f32 v35, v143, v142, v123
	v_max_f32_e64 v30, |v26|, |v27|
	v_max3_f32 v30, |v24|, |v25|, v30
	v_max3_f32 v30, |v28|, |v67|, v30
	v_max3_f32 v30, |v29|, |v31|, v30
	v_max3_f32 v30, |v1|, |v59|, v30
	v_max3_f32 v30, |v3|, |v23|, v30
	v_max3_f32 v30, |v20|, |v21|, v30
	v_max3_f32 v0, |v2|, |v35|, v30
	s_nop 1
	v_mov_b32_dpp v22, v0 row_ror:8 row_mask:0xf bank_mask:0xf bound_ctrl:1
	v_max_f32_e32 v22, v22, v22
	v_max_f32_e32 v0, v0, v22
	s_nop 1
	v_mov_b32_dpp v22, v0 row_ror:4 row_mask:0xf bank_mask:0xf bound_ctrl:1
	v_max_f32_e32 v22, v22, v22
	v_max_f32_e32 v0, v0, v22
	s_nop 1
	v_mov_b32_dpp v22, v0 row_ror:2 row_mask:0xf bank_mask:0xf bound_ctrl:1
	v_max_f32_e32 v22, v22, v22
	v_max_f32_e32 v0, v0, v22
	s_nop 1
	v_mov_b32_dpp v22, v0 row_ror:1 row_mask:0xf bank_mask:0xf bound_ctrl:1
	v_max_f32_e32 v22, v22, v22
	v_max_f32_e32 v0, v0, v22
	ds_bpermute_b32 v22, v62, v0
	s_waitcnt lgkmcnt(0)
	v_max_f32_e32 v22, v22, v22
	v_max_f32_e32 v0, v0, v22
	ds_bpermute_b32 v22, v63, v0
	s_waitcnt lgkmcnt(0)
	v_max_f32_e32 v22, v22, v22
	v_max_f32_e32 v0, v0, v22
	v_div_scale_f32 v22, s[16:17], v0, v0, s20
	v_rcp_f32_e32 v30, v22
	v_cmp_lt_f32_e64 s[10:11], 0, v0
	v_fma_f32 v32, -v22, v30, 1.0
	v_fmac_f32_e32 v30, v32, v30
	v_div_scale_f32 v32, vcc, s20, v0, s20
	v_mul_f32_e32 v33, v32, v30
	v_fma_f32 v34, -v22, v33, v32
	v_fmac_f32_e32 v33, v34, v30
	v_fma_f32 v22, -v22, v33, v32
	v_div_fmas_f32 v22, v22, v30, v33
	v_div_fixup_f32 v22, v22, v0, s20
	v_cndmask_b32_e64 v22, 1.0, v22, s[10:11]
	v_mul_f32_e32 v24, v24, v22
	v_mul_f32_e32 v25, v25, v22
	v_mov_b32_e32 v30, 0
	v_cvt_pk_fp8_f32 v30, v24, v25
	v_mul_f32_e32 v24, v26, v22
	v_mul_f32_e32 v25, v27, v22
	v_mov_b32_e32 v26, 0
	v_cvt_pk_fp8_f32 v30, v24, v25 op_sel:[0,0,1]
	v_mul_f32_e32 v24, v28, v22
	v_mul_f32_e32 v25, v67, v22
	v_cvt_pk_fp8_f32 v26, v24, v25
	v_mul_f32_e32 v24, v29, v22
	v_mul_f32_e32 v25, v31, v22
	v_mul_f32_e32 v1, v1, v22
	v_cvt_pk_fp8_f32 v26, v24, v25 op_sel:[0,0,1]
	v_mul_f32_e32 v24, v59, v22
	v_mov_b32_e32 v25, 0
	v_cvt_pk_fp8_f32 v25, v1, v24
	v_mul_f32_e32 v1, v3, v22
	v_mul_f32_e32 v3, v23, v22
	global_store_dword v[46:47], v30, off
	v_cvt_pk_fp8_f32 v25, v1, v3 op_sel:[0,0,1]
	v_mul_f32_e32 v1, v20, v22
	v_mul_f32_e32 v3, v21, v22
	v_mov_b32_e32 v20, 0
	v_cvt_pk_fp8_f32 v20, v1, v3
	v_mul_f32_e32 v1, v2, v22
	v_mul_f32_e32 v2, v35, v22
	global_store_dword v[46:47], v26, off offset:256
	v_cvt_pk_fp8_f32 v20, v1, v2 op_sel:[0,0,1]
	global_store_dword v[46:47], v25, off offset:512
	global_store_dword v[46:47], v20, off offset:768
	s_and_saveexec_b64 s[16:17], s[6:7]
	s_cbranch_execz .LBB0_209
	v_mul_f32_e32 v0, 0x3b924925, v0
	v_cndmask_b32_e64 v0, 1.0, v0, s[10:11]
	global_store_dword v[44:45], v0, off
	s_branch .LBB0_209

.LBB0_286:
	v_add_u32_e32 v2, s8, v193
	v_ashrrev_i32_e32 v3, 31, v2
	v_or_b32_e32 v0, s6, v196
	v_lshl_add_u64 v[6:7], v[2:3], 2, s[54:55]
	v_ashrrev_i32_e32 v1, 31, v0
	global_load_dword v24, v[6:7], off
	v_lshl_add_u64 v[4:5], v[0:1], 2, s[56:57]
	global_load_dwordx4 v[8:11], v[4:5], off
	global_load_dwordx4 v[12:15], v[4:5], off offset:16
	global_load_dwordx4 v[16:19], v[4:5], off offset:32
	global_load_dwordx4 v[20:23], v[4:5], off offset:48
	global_load_dword v218, v[6:7], off offset:64
	global_load_dword v219, v[6:7], off offset:128
	global_load_dword v220, v[6:7], off offset:192
	global_load_dwordx4 v[222:225], v[4:5], off
	global_load_dwordx4 v[226:229], v[4:5], off offset:16
	global_load_dwordx4 v[230:233], v[4:5], off offset:32
	global_load_dwordx4 v[234:237], v[4:5], off offset:48
	s_cmpk_gt_u32 s6, 0xcff
	s_movk_i32 s6, 0xbff
	s_cselect_b64 s[8:9], -1, 0
	s_cmpk_gt_u32 s14, 0x15ff
	v_cmp_lt_i32_e64 s[6:7], s6, v0
	v_mov_b32_e32 v142, v0
	s_cselect_b64 s[12:13], -1, 0
	s_waitcnt vmcnt(4)
	v_pk_mul_f32 v[26:27], v[124:125], v[24:25] op_sel_hi:[1,0]
	v_pk_mul_f32 v[28:29], v[126:127], v[24:25] op_sel_hi:[1,0]
	v_pk_mul_f32 v[30:31], v[120:121], v[24:25] op_sel_hi:[1,0]
	v_pk_mul_f32 v[32:33], v[122:123], v[24:25] op_sel_hi:[1,0]
	v_pk_mul_f32 v[34:35], v[116:117], v[24:25] op_sel_hi:[1,0]
	v_pk_mul_f32 v[36:37], v[118:119], v[24:25] op_sel_hi:[1,0]
	v_pk_mul_f32 v[38:39], v[112:113], v[24:25] op_sel_hi:[1,0]
	v_pk_mul_f32 v[24:25], v[114:115], v[24:25] op_sel_hi:[1,0]
	s_waitcnt vmcnt(3)
	v_pk_mul_f32 v[8:9], v[26:27], v[8:9]
	v_pk_mul_f32 v[10:11], v[28:29], v[10:11]
	s_waitcnt vmcnt(2)
	v_pk_mul_f32 v[12:13], v[30:31], v[12:13]
	v_pk_mul_f32 v[14:15], v[32:33], v[14:15]
	s_waitcnt vmcnt(1)
	v_pk_mul_f32 v[16:17], v[34:35], v[16:17]
	v_pk_mul_f32 v[18:19], v[36:37], v[18:19]
	s_waitcnt vmcnt(0)
	v_pk_mul_f32 v[20:21], v[38:39], v[20:21]
	v_pk_mul_f32 v[22:23], v[24:25], v[22:23]
	s_and_saveexec_b64 s[14:15], s[6:7]
	s_xor_b64 s[14:15], exec, s[14:15]
	s_cbranch_execz .LBB0_295
	s_mov_b64 s[16:17], -1
	s_and_b64 vcc, exec, s[8:9]
	s_cbranch_vccz .LBB0_293
	s_andn2_b64 vcc, exec, s[12:13]
	s_cbranch_vccnz .LBB0_290
	v_mul_f32_e32 v24, 0xbfb8aa3b, v8
	v_mul_f32_e32 v25, 0xbfb8aa3b, v9
	v_exp_f32_e32 v24, v24
	v_exp_f32_e32 v25, v25
	v_readlane_b32 s36, v247, 2
	v_readlane_b32 s40, v247, 6
	v_readlane_b32 s41, v247, 7
	v_pk_add_f32 v[26:27], v[24:25], 1.0 op_sel_hi:[1,0]
	v_readlane_b32 s37, v247, 3
	v_div_scale_f32 v24, s[16:17], v27, v27, 1.0
	v_rcp_f32_e32 v25, v24
	v_readlane_b32 s38, v247, 4
	v_readlane_b32 s39, v247, 5
	v_readlane_b32 s42, v247, 8
	v_fma_f32 v28, -v24, v25, 1.0
	v_fmac_f32_e32 v25, v28, v25
	v_div_scale_f32 v28, vcc, 1.0, v27, 1.0
	v_mul_f32_e32 v29, v28, v25
	v_fma_f32 v30, -v24, v29, v28
	v_fmac_f32_e32 v29, v30, v25
	v_fma_f32 v24, -v24, v29, v28
	v_div_fmas_f32 v24, v24, v25, v29
	v_div_scale_f32 v25, s[16:17], v26, v26, 1.0
	v_div_fixup_f32 v24, v24, v27, 1.0
	v_rcp_f32_e32 v27, v25
	v_readlane_b32 s43, v247, 9
	v_fma_f32 v28, -v25, v27, 1.0
	v_fmac_f32_e32 v27, v28, v27
	v_div_scale_f32 v28, vcc, 1.0, v26, 1.0
	v_mul_f32_e32 v29, v28, v27
	v_fma_f32 v30, -v25, v29, v28
	v_fmac_f32_e32 v29, v30, v27
	v_fma_f32 v25, -v25, v29, v28
	v_div_fmas_f32 v25, v25, v27, v29
	v_div_fixup_f32 v25, v25, v26, 1.0
	v_mul_f32_e32 v26, 0xbfb8aa3b, v10
	v_mul_f32_e32 v27, 0xbfb8aa3b, v11
	v_exp_f32_e32 v26, v26
	v_exp_f32_e32 v27, v27
	v_cvt_pk_bf16_f32 v24, v25, v24
	v_pk_add_f32 v[28:29], v[26:27], 1.0 op_sel_hi:[1,0]
	s_nop 0
	v_div_scale_f32 v26, s[16:17], v29, v29, 1.0
	v_rcp_f32_e32 v27, v26
	s_nop 0
	v_fma_f32 v30, -v26, v27, 1.0
	v_fmac_f32_e32 v27, v30, v27
	v_div_scale_f32 v30, vcc, 1.0, v29, 1.0
	v_mul_f32_e32 v31, v30, v27
	v_fma_f32 v32, -v26, v31, v30
	v_fmac_f32_e32 v31, v32, v27
	v_fma_f32 v26, -v26, v31, v30
	v_div_fmas_f32 v26, v26, v27, v31
	v_div_scale_f32 v27, s[16:17], v28, v28, 1.0
	v_div_fixup_f32 v26, v26, v29, 1.0
	v_rcp_f32_e32 v29, v27
	s_nop 0
	v_fma_f32 v30, -v27, v29, 1.0
	v_fmac_f32_e32 v29, v30, v29
	v_div_scale_f32 v30, vcc, 1.0, v28, 1.0
	v_mul_f32_e32 v31, v30, v29
	v_fma_f32 v32, -v27, v31, v30
	v_fmac_f32_e32 v31, v32, v29
	v_fma_f32 v27, -v27, v31, v30
	v_div_fmas_f32 v27, v27, v29, v31
	v_div_fixup_f32 v27, v27, v28, 1.0
	v_mul_f32_e32 v28, 0xbfb8aa3b, v12
	v_mul_f32_e32 v29, 0xbfb8aa3b, v13
	v_exp_f32_e32 v28, v28
	v_exp_f32_e32 v29, v29
	v_cvt_pk_bf16_f32 v25, v27, v26
	v_pk_add_f32 v[28:29], v[28:29], 1.0 op_sel_hi:[1,0]
	s_nop 0
	v_div_scale_f32 v30, s[16:17], v29, v29, 1.0
	v_rcp_f32_e32 v31, v30
	s_nop 0
	v_fma_f32 v32, -v30, v31, 1.0
	v_fmac_f32_e32 v31, v32, v31
	v_div_scale_f32 v32, vcc, 1.0, v29, 1.0
	v_mul_f32_e32 v33, v32, v31
	v_fma_f32 v34, -v30, v33, v32
	v_fmac_f32_e32 v33, v34, v31
	v_fma_f32 v30, -v30, v33, v32
	v_div_fmas_f32 v30, v30, v31, v33
	v_div_fixup_f32 v30, v30, v29, 1.0
	v_div_scale_f32 v29, s[16:17], v28, v28, 1.0
	v_rcp_f32_e32 v31, v29
	s_nop 0
	v_fma_f32 v32, -v29, v31, 1.0
	v_fmac_f32_e32 v31, v32, v31
	v_div_scale_f32 v32, vcc, 1.0, v28, 1.0
	v_mul_f32_e32 v33, v32, v31
	v_fma_f32 v34, -v29, v33, v32
	v_fmac_f32_e32 v33, v34, v31
	v_fma_f32 v29, -v29, v33, v32
	v_div_fmas_f32 v29, v29, v31, v33
	v_div_fixup_f32 v31, v29, v28, 1.0
	v_mul_f32_e32 v28, 0xbfb8aa3b, v14
	v_mul_f32_e32 v29, 0xbfb8aa3b, v15
	v_exp_f32_e32 v28, v28
	v_exp_f32_e32 v29, v29
	v_cvt_pk_bf16_f32 v26, v31, v30
	v_pk_add_f32 v[28:29], v[28:29], 1.0 op_sel_hi:[1,0]
	s_nop 0
	v_div_scale_f32 v32, s[16:17], v29, v29, 1.0
	v_rcp_f32_e32 v33, v32
	s_nop 0
	v_fma_f32 v34, -v32, v33, 1.0
	v_fmac_f32_e32 v33, v34, v33
	v_div_scale_f32 v34, vcc, 1.0, v29, 1.0
	v_mul_f32_e32 v35, v34, v33
	v_fma_f32 v36, -v32, v35, v34
	v_fmac_f32_e32 v35, v36, v33
	v_fma_f32 v32, -v32, v35, v34
	v_div_fmas_f32 v32, v32, v33, v35
	v_div_fixup_f32 v34, v32, v29, 1.0
	v_div_scale_f32 v29, s[16:17], v28, v28, 1.0
	v_rcp_f32_e32 v32, v29
	s_nop 0
	v_fma_f32 v33, -v29, v32, 1.0
	v_fmac_f32_e32 v32, v33, v32
	v_div_scale_f32 v33, vcc, 1.0, v28, 1.0
	v_mul_f32_e32 v35, v33, v32
	v_fma_f32 v36, -v29, v35, v33
	v_fmac_f32_e32 v35, v36, v32
	v_fma_f32 v29, -v29, v35, v33
	v_div_fmas_f32 v29, v29, v32, v35
	v_div_fixup_f32 v35, v29, v28, 1.0
	v_mul_f32_e32 v28, 0xbfb8aa3b, v16
	v_mul_f32_e32 v29, 0xbfb8aa3b, v17
	v_exp_f32_e32 v28, v28
	v_exp_f32_e32 v29, v29
	v_cvt_pk_bf16_f32 v27, v35, v34
	v_pk_add_f32 v[28:29], v[28:29], 1.0 op_sel_hi:[1,0]
	s_nop 0
	v_div_scale_f32 v32, s[16:17], v29, v29, 1.0
	v_rcp_f32_e32 v33, v32
	s_nop 0
	v_fma_f32 v36, -v32, v33, 1.0
	v_fmac_f32_e32 v33, v36, v33
	v_div_scale_f32 v36, vcc, 1.0, v29, 1.0
	v_mul_f32_e32 v37, v36, v33
	v_fma_f32 v38, -v32, v37, v36
	v_fmac_f32_e32 v37, v38, v33
	v_fma_f32 v32, -v32, v37, v36
	v_div_fmas_f32 v32, v32, v33, v37
	v_div_fixup_f32 v36, v32, v29, 1.0
	v_div_scale_f32 v29, s[16:17], v28, v28, 1.0
	v_rcp_f32_e32 v32, v29
	s_nop 0
	v_fma_f32 v33, -v29, v32, 1.0
	v_fmac_f32_e32 v32, v33, v32
	v_div_scale_f32 v33, vcc, 1.0, v28, 1.0
	v_mul_f32_e32 v37, v33, v32
	v_fma_f32 v38, -v29, v37, v33
	v_fmac_f32_e32 v37, v38, v32
	v_fma_f32 v29, -v29, v37, v33
	v_div_fmas_f32 v29, v29, v32, v37
	v_div_fixup_f32 v37, v29, v28, 1.0
	v_mul_f32_e32 v28, 0xbfb8aa3b, v18
	v_mul_f32_e32 v29, 0xbfb8aa3b, v19
	v_exp_f32_e32 v28, v28
	v_exp_f32_e32 v29, v29
	s_nop 0
	v_pk_add_f32 v[28:29], v[28:29], 1.0 op_sel_hi:[1,0]
	s_nop 0
	v_div_scale_f32 v32, s[16:17], v29, v29, 1.0
	v_rcp_f32_e32 v33, v32
	s_nop 0
	v_fma_f32 v38, -v32, v33, 1.0
	v_fmac_f32_e32 v33, v38, v33
	v_div_scale_f32 v38, vcc, 1.0, v29, 1.0
	v_mul_f32_e32 v39, v38, v33
	v_fma_f32 v40, -v32, v39, v38
	v_fmac_f32_e32 v39, v40, v33
	v_fma_f32 v32, -v32, v39, v38
	v_div_fmas_f32 v32, v32, v33, v39
	v_div_fixup_f32 v38, v32, v29, 1.0
	v_div_scale_f32 v29, s[16:17], v28, v28, 1.0
	v_rcp_f32_e32 v32, v29
	s_nop 0
	v_fma_f32 v33, -v29, v32, 1.0
	v_fmac_f32_e32 v32, v33, v32
	v_div_scale_f32 v33, vcc, 1.0, v28, 1.0
	v_mul_f32_e32 v39, v33, v32
	v_fma_f32 v40, -v29, v39, v33
	v_fmac_f32_e32 v39, v40, v32
	v_fma_f32 v29, -v29, v39, v33
	v_div_fmas_f32 v29, v29, v32, v39
	v_div_fixup_f32 v39, v29, v28, 1.0
	v_mul_f32_e32 v28, 0xbfb8aa3b, v20
	v_mul_f32_e32 v29, 0xbfb8aa3b, v21
	v_exp_f32_e32 v28, v28
	v_exp_f32_e32 v29, v29
	s_nop 0
	v_pk_add_f32 v[28:29], v[28:29], 1.0 op_sel_hi:[1,0]
	s_nop 0
	v_div_scale_f32 v32, s[16:17], v29, v29, 1.0
	v_rcp_f32_e32 v33, v32
	s_nop 0
	v_fma_f32 v40, -v32, v33, 1.0
	v_fmac_f32_e32 v33, v40, v33
	v_div_scale_f32 v40, vcc, 1.0, v29, 1.0
	v_mul_f32_e32 v41, v40, v33
	v_fma_f32 v42, -v32, v41, v40
	v_fmac_f32_e32 v41, v42, v33
	v_fma_f32 v32, -v32, v41, v40
	v_div_fmas_f32 v32, v32, v33, v41
	v_div_fixup_f32 v40, v32, v29, 1.0
	v_div_scale_f32 v29, s[16:17], v28, v28, 1.0
	v_rcp_f32_e32 v32, v29
	s_nop 0
	v_fma_f32 v33, -v29, v32, 1.0
	v_fmac_f32_e32 v32, v33, v32
	v_div_scale_f32 v33, vcc, 1.0, v28, 1.0
	v_mul_f32_e32 v41, v33, v32
	v_fma_f32 v42, -v29, v41, v33
	v_fmac_f32_e32 v41, v42, v32
	v_fma_f32 v29, -v29, v41, v33
	v_div_fmas_f32 v29, v29, v32, v41
	v_div_fixup_f32 v41, v29, v28, 1.0
	v_mul_f32_e32 v28, 0xbfb8aa3b, v22
	v_mul_f32_e32 v29, 0xbfb8aa3b, v23
	v_exp_f32_e32 v28, v28
	v_exp_f32_e32 v29, v29
	v_cvt_pk_bf16_f32 v30, v41, v40
	v_pk_add_f32 v[28:29], v[28:29], 1.0 op_sel_hi:[1,0]
	s_nop 0
	v_div_scale_f32 v32, s[16:17], v29, v29, 1.0
	v_rcp_f32_e32 v33, v32
	s_nop 0
	v_fma_f32 v42, -v32, v33, 1.0
	v_fmac_f32_e32 v33, v42, v33
	v_div_scale_f32 v42, vcc, 1.0, v29, 1.0
	v_mul_f32_e32 v43, v42, v33
	v_fma_f32 v44, -v32, v43, v42
	v_fmac_f32_e32 v43, v44, v33
	v_fma_f32 v32, -v32, v43, v42
	v_div_fmas_f32 v32, v32, v33, v43
	v_div_fixup_f32 v42, v32, v29, 1.0
	v_div_scale_f32 v29, s[16:17], v28, v28, 1.0
	v_rcp_f32_e32 v32, v29
	s_mov_b64 s[16:17], 0
	v_fma_f32 v33, -v29, v32, 1.0
	v_fmac_f32_e32 v32, v33, v32
	v_div_scale_f32 v33, vcc, 1.0, v28, 1.0
	v_mul_f32_e32 v43, v33, v32
	v_fma_f32 v44, -v29, v43, v33
	v_fmac_f32_e32 v43, v44, v32
	v_fma_f32 v29, -v29, v43, v33
	v_div_fmas_f32 v29, v29, v32, v43
	v_div_fixup_f32 v43, v29, v28, 1.0
	v_lshlrev_b64 v[28:29], 12, v[2:3]
	v_lshl_add_u64 v[28:29], s[40:41], 0, v[28:29]
	v_lshl_add_u64 v[32:33], v[142:143], 1, v[28:29]
	v_add_co_u32_e32 v32, vcc, 0xffffe000, v32
	v_cvt_pk_bf16_f32 v28, v37, v36
	s_nop 0
	v_addc_co_u32_e32 v33, vcc, -1, v33, vcc
	v_cvt_pk_bf16_f32 v29, v39, v38
	v_cvt_pk_bf16_f32 v31, v43, v42
	global_store_dwordx4 v[32:33], v[24:27], off offset:-3072
	global_store_dwordx4 v[32:33], v[28:31], off offset:-3056

.LBB0_297:
	s_or_b64 exec, exec, s[14:15]
	s_nop 1
	v_mov_b32_e32 v26, v218
	v_mov_b32_e32 v25, v237
	v_mov_b32_e32 v24, v236
	v_mov_b32_e32 v23, v235
	v_mov_b32_e32 v22, v234
	v_mov_b32_e32 v21, v233
	v_mov_b32_e32 v20, v232
	v_mov_b32_e32 v19, v231
	v_mov_b32_e32 v18, v230
	v_mov_b32_e32 v17, v229
	v_mov_b32_e32 v16, v228
	v_mov_b32_e32 v15, v227
	v_mov_b32_e32 v14, v226
	v_mov_b32_e32 v13, v225
	v_mov_b32_e32 v12, v224
	v_mov_b32_e32 v11, v223
	v_mov_b32_e32 v10, v222
	v_or_b32_e32 v8, 16, v2
	v_cndmask_b32_e64 v3, 0, 1, s[8:9]
	v_ashrrev_i32_e32 v9, 31, v8
	v_cmp_ne_u32_e64 s[8:9], 1, v3
	v_pk_mul_f32 v[28:29], v[108:109], v[26:27] op_sel_hi:[1,0]
	v_pk_mul_f32 v[10:11], v[28:29], v[10:11]
	v_pk_mul_f32 v[28:29], v[110:111], v[26:27] op_sel_hi:[1,0]
	s_nop 0
	v_pk_mul_f32 v[12:13], v[28:29], v[12:13]
	v_pk_mul_f32 v[28:29], v[104:105], v[26:27] op_sel_hi:[1,0]
	s_nop 0
	v_pk_mul_f32 v[14:15], v[28:29], v[14:15]
	v_pk_mul_f32 v[28:29], v[106:107], v[26:27] op_sel_hi:[1,0]
	s_nop 0
	v_pk_mul_f32 v[16:17], v[28:29], v[16:17]
	v_pk_mul_f32 v[28:29], v[100:101], v[26:27] op_sel_hi:[1,0]
	s_nop 0
	v_pk_mul_f32 v[18:19], v[28:29], v[18:19]
	v_pk_mul_f32 v[28:29], v[102:103], v[26:27] op_sel_hi:[1,0]
	s_nop 0
	v_pk_mul_f32 v[20:21], v[28:29], v[20:21]
	v_pk_mul_f32 v[28:29], v[96:97], v[26:27] op_sel_hi:[1,0]
	v_pk_mul_f32 v[26:27], v[98:99], v[26:27] op_sel_hi:[1,0]
	v_pk_mul_f32 v[22:23], v[28:29], v[22:23]
	v_pk_mul_f32 v[24:25], v[26:27], v[24:25]
	s_and_saveexec_b64 s[14:15], s[6:7]
	s_xor_b64 s[14:15], exec, s[14:15]
	s_cbranch_execz .LBB0_306
	s_and_b64 vcc, exec, s[8:9]
	s_mov_b64 s[16:17], -1
	s_cbranch_vccnz .LBB0_304
	s_andn2_b64 vcc, exec, s[12:13]
	s_cbranch_vccnz .LBB0_301
	v_mul_f32_e32 v3, 0xbfb8aa3b, v10
	v_exp_f32_e32 v26, v3
	v_mul_f32_e32 v3, 0xbfb8aa3b, v11
	v_exp_f32_e32 v27, v3
	v_readlane_b32 s36, v247, 2
	v_readlane_b32 s40, v247, 6
	v_readlane_b32 s41, v247, 7
	v_pk_add_f32 v[26:27], v[26:27], 1.0 op_sel_hi:[1,0]
	v_readlane_b32 s37, v247, 3
	v_div_scale_f32 v3, s[16:17], v27, v27, 1.0
	v_rcp_f32_e32 v28, v3
	v_readlane_b32 s38, v247, 4
	v_readlane_b32 s39, v247, 5
	v_readlane_b32 s42, v247, 8
	v_fma_f32 v29, -v3, v28, 1.0
	v_fmac_f32_e32 v28, v29, v28
	v_div_scale_f32 v29, vcc, 1.0, v27, 1.0
	v_mul_f32_e32 v30, v29, v28
	v_fma_f32 v31, -v3, v30, v29
	v_fmac_f32_e32 v30, v31, v28
	v_fma_f32 v3, -v3, v30, v29
	v_div_fmas_f32 v3, v3, v28, v30
	v_div_fixup_f32 v3, v3, v27, 1.0
	v_div_scale_f32 v27, s[16:17], v26, v26, 1.0
	v_rcp_f32_e32 v28, v27
	v_readlane_b32 s43, v247, 9
	v_fma_f32 v29, -v27, v28, 1.0
	v_fmac_f32_e32 v28, v29, v28
	v_div_scale_f32 v29, vcc, 1.0, v26, 1.0
	v_mul_f32_e32 v30, v29, v28
	v_fma_f32 v31, -v27, v30, v29
	v_fmac_f32_e32 v30, v31, v28
	v_fma_f32 v27, -v27, v30, v29
	v_div_fmas_f32 v27, v27, v28, v30
	v_div_fixup_f32 v26, v27, v26, 1.0
	v_mul_f32_e32 v27, 0xbfb8aa3b, v12
	v_exp_f32_e32 v28, v27
	v_mul_f32_e32 v27, 0xbfb8aa3b, v13
	v_exp_f32_e32 v29, v27
	v_cvt_pk_bf16_f32 v26, v26, v3
	v_pk_add_f32 v[28:29], v[28:29], 1.0 op_sel_hi:[1,0]
	s_nop 0
	v_div_scale_f32 v27, s[16:17], v29, v29, 1.0
	v_rcp_f32_e32 v30, v27
	s_nop 0
	v_fma_f32 v31, -v27, v30, 1.0
	v_fmac_f32_e32 v30, v31, v30
	v_div_scale_f32 v31, vcc, 1.0, v29, 1.0
	v_mul_f32_e32 v32, v31, v30
	v_fma_f32 v33, -v27, v32, v31
	v_fmac_f32_e32 v32, v33, v30
	v_fma_f32 v27, -v27, v32, v31
	v_div_fmas_f32 v27, v27, v30, v32
	v_div_fixup_f32 v27, v27, v29, 1.0
	v_div_scale_f32 v29, s[16:17], v28, v28, 1.0
	v_rcp_f32_e32 v30, v29
	s_nop 0
	v_fma_f32 v31, -v29, v30, 1.0
	v_fmac_f32_e32 v30, v31, v30
	v_div_scale_f32 v31, vcc, 1.0, v28, 1.0
	v_mul_f32_e32 v32, v31, v30
	v_fma_f32 v33, -v29, v32, v31
	v_fmac_f32_e32 v32, v33, v30
	v_fma_f32 v29, -v29, v32, v31
	v_div_fmas_f32 v29, v29, v30, v32
	v_div_fixup_f32 v28, v29, v28, 1.0
	v_mul_f32_e32 v29, 0xbfb8aa3b, v14
	v_exp_f32_e32 v30, v29
	v_mul_f32_e32 v29, 0xbfb8aa3b, v15
	v_exp_f32_e32 v31, v29
	v_cvt_pk_bf16_f32 v27, v28, v27
	v_pk_add_f32 v[30:31], v[30:31], 1.0 op_sel_hi:[1,0]
	s_nop 0
	v_div_scale_f32 v29, s[16:17], v31, v31, 1.0
	v_rcp_f32_e32 v32, v29
	s_nop 0
	v_fma_f32 v33, -v29, v32, 1.0
	v_fmac_f32_e32 v32, v33, v32
	v_div_scale_f32 v33, vcc, 1.0, v31, 1.0
	v_mul_f32_e32 v34, v33, v32
	v_fma_f32 v35, -v29, v34, v33
	v_fmac_f32_e32 v34, v35, v32
	v_fma_f32 v29, -v29, v34, v33
	v_div_fmas_f32 v29, v29, v32, v34
	v_div_fixup_f32 v29, v29, v31, 1.0
	v_div_scale_f32 v31, s[16:17], v30, v30, 1.0
	v_rcp_f32_e32 v32, v31
	s_nop 0
	v_fma_f32 v33, -v31, v32, 1.0
	v_fmac_f32_e32 v32, v33, v32
	v_div_scale_f32 v33, vcc, 1.0, v30, 1.0
	v_mul_f32_e32 v34, v33, v32
	v_fma_f32 v35, -v31, v34, v33
	v_fmac_f32_e32 v34, v35, v32
	v_fma_f32 v31, -v31, v34, v33
	v_div_fmas_f32 v31, v31, v32, v34
	v_div_fixup_f32 v32, v31, v30, 1.0
	v_mul_f32_e32 v30, 0xbfb8aa3b, v16
	v_mul_f32_e32 v31, 0xbfb8aa3b, v17
	v_exp_f32_e32 v30, v30
	v_exp_f32_e32 v31, v31
	v_cvt_pk_bf16_f32 v28, v32, v29
	v_pk_add_f32 v[30:31], v[30:31], 1.0 op_sel_hi:[1,0]
	s_nop 0
	v_div_scale_f32 v33, s[16:17], v31, v31, 1.0
	v_rcp_f32_e32 v34, v33
	s_nop 0
	v_fma_f32 v35, -v33, v34, 1.0
	v_fmac_f32_e32 v34, v35, v34
	v_div_scale_f32 v35, vcc, 1.0, v31, 1.0
	v_mul_f32_e32 v36, v35, v34
	v_fma_f32 v37, -v33, v36, v35
	v_fmac_f32_e32 v36, v37, v34
	v_fma_f32 v33, -v33, v36, v35
	v_div_fmas_f32 v33, v33, v34, v36
	v_div_fixup_f32 v33, v33, v31, 1.0
	v_div_scale_f32 v31, s[16:17], v30, v30, 1.0
	v_rcp_f32_e32 v34, v31
	s_nop 0
	v_fma_f32 v35, -v31, v34, 1.0
	v_fmac_f32_e32 v34, v35, v34
	v_div_scale_f32 v35, vcc, 1.0, v30, 1.0
	v_mul_f32_e32 v36, v35, v34
	v_fma_f32 v37, -v31, v36, v35
	v_fmac_f32_e32 v36, v37, v34
	v_fma_f32 v31, -v31, v36, v35
	v_div_fmas_f32 v31, v31, v34, v36
	v_div_fixup_f32 v36, v31, v30, 1.0
	v_mul_f32_e32 v30, 0xbfb8aa3b, v18
	v_mul_f32_e32 v31, 0xbfb8aa3b, v19
	v_exp_f32_e32 v30, v30
	v_exp_f32_e32 v31, v31
	v_cvt_pk_bf16_f32 v29, v36, v33
	v_pk_add_f32 v[30:31], v[30:31], 1.0 op_sel_hi:[1,0]
	s_nop 0
	v_div_scale_f32 v34, s[16:17], v31, v31, 1.0
	v_rcp_f32_e32 v35, v34
	s_nop 0
	v_fma_f32 v37, -v34, v35, 1.0
	v_fmac_f32_e32 v35, v37, v35
	v_div_scale_f32 v37, vcc, 1.0, v31, 1.0
	v_mul_f32_e32 v38, v37, v35
	v_fma_f32 v39, -v34, v38, v37
	v_fmac_f32_e32 v38, v39, v35
	v_fma_f32 v34, -v34, v38, v37
	v_div_fmas_f32 v34, v34, v35, v38
	v_div_fixup_f32 v37, v34, v31, 1.0
	v_div_scale_f32 v31, s[16:17], v30, v30, 1.0
	v_rcp_f32_e32 v34, v31
	s_nop 0
	v_fma_f32 v35, -v31, v34, 1.0
	v_fmac_f32_e32 v34, v35, v34
	v_div_scale_f32 v35, vcc, 1.0, v30, 1.0
	v_mul_f32_e32 v38, v35, v34
	v_fma_f32 v39, -v31, v38, v35
	v_fmac_f32_e32 v38, v39, v34
	v_fma_f32 v31, -v31, v38, v35
	v_div_fmas_f32 v31, v31, v34, v38
	v_div_fixup_f32 v38, v31, v30, 1.0
	v_mul_f32_e32 v30, 0xbfb8aa3b, v20
	v_mul_f32_e32 v31, 0xbfb8aa3b, v21
	v_exp_f32_e32 v30, v30
	v_exp_f32_e32 v31, v31
	s_nop 0
	v_pk_add_f32 v[30:31], v[30:31], 1.0 op_sel_hi:[1,0]
	s_nop 0
	v_div_scale_f32 v34, s[16:17], v31, v31, 1.0
	v_rcp_f32_e32 v35, v34
	s_nop 0
	v_fma_f32 v39, -v34, v35, 1.0
	v_fmac_f32_e32 v35, v39, v35
	v_div_scale_f32 v39, vcc, 1.0, v31, 1.0
	v_mul_f32_e32 v40, v39, v35
	v_fma_f32 v41, -v34, v40, v39
	v_fmac_f32_e32 v40, v41, v35
	v_fma_f32 v34, -v34, v40, v39
	v_div_fmas_f32 v34, v34, v35, v40
	v_div_fixup_f32 v39, v34, v31, 1.0
	v_div_scale_f32 v31, s[16:17], v30, v30, 1.0
	v_rcp_f32_e32 v34, v31
	s_nop 0
	v_fma_f32 v35, -v31, v34, 1.0
	v_fmac_f32_e32 v34, v35, v34
	v_div_scale_f32 v35, vcc, 1.0, v30, 1.0
	v_mul_f32_e32 v40, v35, v34
	v_fma_f32 v41, -v31, v40, v35
	v_fmac_f32_e32 v40, v41, v34
	v_fma_f32 v31, -v31, v40, v35
	v_div_fmas_f32 v31, v31, v34, v40
	v_div_fixup_f32 v40, v31, v30, 1.0
	v_mul_f32_e32 v30, 0xbfb8aa3b, v22
	v_mul_f32_e32 v31, 0xbfb8aa3b, v23
	v_exp_f32_e32 v30, v30
	v_exp_f32_e32 v31, v31
	s_nop 0
	v_pk_add_f32 v[30:31], v[30:31], 1.0 op_sel_hi:[1,0]
	s_nop 0
	v_div_scale_f32 v34, s[16:17], v31, v31, 1.0
	v_rcp_f32_e32 v35, v34
	s_nop 0
	v_fma_f32 v41, -v34, v35, 1.0
	v_fmac_f32_e32 v35, v41, v35
	v_div_scale_f32 v41, vcc, 1.0, v31, 1.0
	v_mul_f32_e32 v42, v41, v35
	v_fma_f32 v43, -v34, v42, v41
	v_fmac_f32_e32 v42, v43, v35
	v_fma_f32 v34, -v34, v42, v41
	v_div_fmas_f32 v34, v34, v35, v42
	v_div_fixup_f32 v41, v34, v31, 1.0
	v_div_scale_f32 v31, s[16:17], v30, v30, 1.0
	v_rcp_f32_e32 v34, v31
	s_nop 0
	v_fma_f32 v35, -v31, v34, 1.0
	v_fmac_f32_e32 v34, v35, v34
	v_div_scale_f32 v35, vcc, 1.0, v30, 1.0
	v_mul_f32_e32 v42, v35, v34
	v_fma_f32 v43, -v31, v42, v35
	v_fmac_f32_e32 v42, v43, v34
	v_fma_f32 v31, -v31, v42, v35
	v_div_fmas_f32 v31, v31, v34, v42
	v_div_fixup_f32 v42, v31, v30, 1.0
	v_mul_f32_e32 v30, 0xbfb8aa3b, v24
	v_mul_f32_e32 v31, 0xbfb8aa3b, v25
	v_exp_f32_e32 v30, v30
	v_exp_f32_e32 v31, v31
	v_cvt_pk_bf16_f32 v32, v42, v41
	v_pk_add_f32 v[30:31], v[30:31], 1.0 op_sel_hi:[1,0]
	s_nop 0
	v_div_scale_f32 v34, s[16:17], v31, v31, 1.0
	v_rcp_f32_e32 v35, v34
	s_nop 0
	v_fma_f32 v43, -v34, v35, 1.0
	v_fmac_f32_e32 v35, v43, v35
	v_div_scale_f32 v43, vcc, 1.0, v31, 1.0
	v_mul_f32_e32 v44, v43, v35
	v_fma_f32 v45, -v34, v44, v43
	v_fmac_f32_e32 v44, v45, v35
	v_fma_f32 v34, -v34, v44, v43
	v_div_fmas_f32 v34, v34, v35, v44
	v_div_fixup_f32 v43, v34, v31, 1.0
	v_div_scale_f32 v31, s[16:17], v30, v30, 1.0
	v_rcp_f32_e32 v34, v31
	s_mov_b64 s[16:17], 0
	v_fma_f32 v35, -v31, v34, 1.0
	v_fmac_f32_e32 v34, v35, v34
	v_div_scale_f32 v35, vcc, 1.0, v30, 1.0
	v_mul_f32_e32 v44, v35, v34
	v_fma_f32 v45, -v31, v44, v35
	v_fmac_f32_e32 v44, v45, v34
	v_fma_f32 v31, -v31, v44, v35
	v_div_fmas_f32 v31, v31, v34, v44
	v_div_fixup_f32 v44, v31, v30, 1.0
	v_lshlrev_b64 v[30:31], 12, v[8:9]
	v_lshl_add_u64 v[30:31], s[40:41], 0, v[30:31]
	v_lshl_add_u64 v[34:35], v[142:143], 1, v[30:31]
	v_add_co_u32_e32 v34, vcc, 0xffffe000, v34
	v_cvt_pk_bf16_f32 v30, v38, v37
	s_nop 0
	v_addc_co_u32_e32 v35, vcc, -1, v35, vcc
	v_cvt_pk_bf16_f32 v31, v40, v39
	v_cvt_pk_bf16_f32 v33, v44, v43
	global_store_dwordx4 v[34:35], v[26:29], off offset:-3072
	global_store_dwordx4 v[34:35], v[30:33], off offset:-3056

.LBB0_308:
	s_or_b64 exec, exec, s[14:15]
	s_nop 1
	v_mov_b32_e32 v26, v219
	v_mov_b32_e32 v25, v237
	v_mov_b32_e32 v24, v236
	v_mov_b32_e32 v23, v235
	v_mov_b32_e32 v22, v234
	v_mov_b32_e32 v21, v233
	v_mov_b32_e32 v20, v232
	v_mov_b32_e32 v19, v231
	v_mov_b32_e32 v18, v230
	v_mov_b32_e32 v17, v229
	v_mov_b32_e32 v16, v228
	v_mov_b32_e32 v15, v227
	v_mov_b32_e32 v14, v226
	v_mov_b32_e32 v13, v225
	v_mov_b32_e32 v12, v224
	v_mov_b32_e32 v11, v223
	v_mov_b32_e32 v10, v222
	v_or_b32_e32 v8, 32, v2
	v_ashrrev_i32_e32 v9, 31, v8
	v_pk_mul_f32 v[28:29], v[92:93], v[26:27] op_sel_hi:[1,0]
	v_pk_mul_f32 v[30:31], v[94:95], v[26:27] op_sel_hi:[1,0]
	v_pk_mul_f32 v[32:33], v[88:89], v[26:27] op_sel_hi:[1,0]
	v_pk_mul_f32 v[34:35], v[90:91], v[26:27] op_sel_hi:[1,0]
	v_pk_mul_f32 v[36:37], v[84:85], v[26:27] op_sel_hi:[1,0]
	v_pk_mul_f32 v[38:39], v[86:87], v[26:27] op_sel_hi:[1,0]
	v_pk_mul_f32 v[40:41], v[80:81], v[26:27] op_sel_hi:[1,0]
	v_pk_mul_f32 v[26:27], v[82:83], v[26:27] op_sel_hi:[1,0]
	v_pk_mul_f32 v[10:11], v[28:29], v[10:11]
	v_pk_mul_f32 v[12:13], v[30:31], v[12:13]
	v_pk_mul_f32 v[14:15], v[32:33], v[14:15]
	v_pk_mul_f32 v[16:17], v[34:35], v[16:17]
	v_pk_mul_f32 v[18:19], v[36:37], v[18:19]
	v_pk_mul_f32 v[20:21], v[38:39], v[20:21]
	v_pk_mul_f32 v[22:23], v[40:41], v[22:23]
	v_pk_mul_f32 v[24:25], v[26:27], v[24:25]
	s_and_saveexec_b64 s[14:15], s[6:7]
	s_xor_b64 s[14:15], exec, s[14:15]
	s_cbranch_execz .LBB0_317
	s_and_b64 vcc, exec, s[8:9]
	s_mov_b64 s[16:17], -1
	s_cbranch_vccnz .LBB0_315
	s_andn2_b64 vcc, exec, s[12:13]
	s_cbranch_vccnz .LBB0_312
	v_mul_f32_e32 v3, 0xbfb8aa3b, v10
	v_exp_f32_e32 v26, v3
	v_mul_f32_e32 v3, 0xbfb8aa3b, v11
	v_exp_f32_e32 v27, v3
	v_readlane_b32 s36, v247, 2
	v_readlane_b32 s40, v247, 6
	v_readlane_b32 s41, v247, 7
	v_pk_add_f32 v[26:27], v[26:27], 1.0 op_sel_hi:[1,0]
	v_readlane_b32 s37, v247, 3
	v_div_scale_f32 v3, s[16:17], v27, v27, 1.0
	v_rcp_f32_e32 v28, v3
	v_readlane_b32 s38, v247, 4
	v_readlane_b32 s39, v247, 5
	v_readlane_b32 s42, v247, 8
	v_fma_f32 v29, -v3, v28, 1.0
	v_fmac_f32_e32 v28, v29, v28
	v_div_scale_f32 v29, vcc, 1.0, v27, 1.0
	v_mul_f32_e32 v30, v29, v28
	v_fma_f32 v31, -v3, v30, v29
	v_fmac_f32_e32 v30, v31, v28
	v_fma_f32 v3, -v3, v30, v29
	v_div_fmas_f32 v3, v3, v28, v30
	v_div_fixup_f32 v3, v3, v27, 1.0
	v_div_scale_f32 v27, s[16:17], v26, v26, 1.0
	v_rcp_f32_e32 v28, v27
	v_readlane_b32 s43, v247, 9
	v_fma_f32 v29, -v27, v28, 1.0
	v_fmac_f32_e32 v28, v29, v28
	v_div_scale_f32 v29, vcc, 1.0, v26, 1.0
	v_mul_f32_e32 v30, v29, v28
	v_fma_f32 v31, -v27, v30, v29
	v_fmac_f32_e32 v30, v31, v28
	v_fma_f32 v27, -v27, v30, v29
	v_div_fmas_f32 v27, v27, v28, v30
	v_div_fixup_f32 v26, v27, v26, 1.0
	v_mul_f32_e32 v27, 0xbfb8aa3b, v12
	v_exp_f32_e32 v28, v27
	v_mul_f32_e32 v27, 0xbfb8aa3b, v13
	v_exp_f32_e32 v29, v27
	v_cvt_pk_bf16_f32 v26, v26, v3
	v_pk_add_f32 v[28:29], v[28:29], 1.0 op_sel_hi:[1,0]
	s_nop 0
	v_div_scale_f32 v27, s[16:17], v29, v29, 1.0
	v_rcp_f32_e32 v30, v27
	s_nop 0
	v_fma_f32 v31, -v27, v30, 1.0
	v_fmac_f32_e32 v30, v31, v30
	v_div_scale_f32 v31, vcc, 1.0, v29, 1.0
	v_mul_f32_e32 v32, v31, v30
	v_fma_f32 v33, -v27, v32, v31
	v_fmac_f32_e32 v32, v33, v30
	v_fma_f32 v27, -v27, v32, v31
	v_div_fmas_f32 v27, v27, v30, v32
	v_div_fixup_f32 v27, v27, v29, 1.0
	v_div_scale_f32 v29, s[16:17], v28, v28, 1.0
	v_rcp_f32_e32 v30, v29
	s_nop 0
	v_fma_f32 v31, -v29, v30, 1.0
	v_fmac_f32_e32 v30, v31, v30
	v_div_scale_f32 v31, vcc, 1.0, v28, 1.0
	v_mul_f32_e32 v32, v31, v30
	v_fma_f32 v33, -v29, v32, v31
	v_fmac_f32_e32 v32, v33, v30
	v_fma_f32 v29, -v29, v32, v31
	v_div_fmas_f32 v29, v29, v30, v32
	v_div_fixup_f32 v28, v29, v28, 1.0
	v_mul_f32_e32 v29, 0xbfb8aa3b, v14
	v_exp_f32_e32 v30, v29
	v_mul_f32_e32 v29, 0xbfb8aa3b, v15
	v_exp_f32_e32 v31, v29
	v_cvt_pk_bf16_f32 v27, v28, v27
	v_pk_add_f32 v[30:31], v[30:31], 1.0 op_sel_hi:[1,0]
	s_nop 0
	v_div_scale_f32 v29, s[16:17], v31, v31, 1.0
	v_rcp_f32_e32 v32, v29
	s_nop 0
	v_fma_f32 v33, -v29, v32, 1.0
	v_fmac_f32_e32 v32, v33, v32
	v_div_scale_f32 v33, vcc, 1.0, v31, 1.0
	v_mul_f32_e32 v34, v33, v32
	v_fma_f32 v35, -v29, v34, v33
	v_fmac_f32_e32 v34, v35, v32
	v_fma_f32 v29, -v29, v34, v33
	v_div_fmas_f32 v29, v29, v32, v34
	v_div_fixup_f32 v29, v29, v31, 1.0
	v_div_scale_f32 v31, s[16:17], v30, v30, 1.0
	v_rcp_f32_e32 v32, v31
	s_nop 0
	v_fma_f32 v33, -v31, v32, 1.0
	v_fmac_f32_e32 v32, v33, v32
	v_div_scale_f32 v33, vcc, 1.0, v30, 1.0
	v_mul_f32_e32 v34, v33, v32
	v_fma_f32 v35, -v31, v34, v33
	v_fmac_f32_e32 v34, v35, v32
	v_fma_f32 v31, -v31, v34, v33
	v_div_fmas_f32 v31, v31, v32, v34
	v_div_fixup_f32 v32, v31, v30, 1.0
	v_mul_f32_e32 v30, 0xbfb8aa3b, v16
	v_mul_f32_e32 v31, 0xbfb8aa3b, v17
	v_exp_f32_e32 v30, v30
	v_exp_f32_e32 v31, v31
	v_cvt_pk_bf16_f32 v28, v32, v29
	v_pk_add_f32 v[30:31], v[30:31], 1.0 op_sel_hi:[1,0]
	s_nop 0
	v_div_scale_f32 v33, s[16:17], v31, v31, 1.0
	v_rcp_f32_e32 v34, v33
	s_nop 0
	v_fma_f32 v35, -v33, v34, 1.0
	v_fmac_f32_e32 v34, v35, v34
	v_div_scale_f32 v35, vcc, 1.0, v31, 1.0
	v_mul_f32_e32 v36, v35, v34
	v_fma_f32 v37, -v33, v36, v35
	v_fmac_f32_e32 v36, v37, v34
	v_fma_f32 v33, -v33, v36, v35
	v_div_fmas_f32 v33, v33, v34, v36
	v_div_fixup_f32 v33, v33, v31, 1.0
	v_div_scale_f32 v31, s[16:17], v30, v30, 1.0
	v_rcp_f32_e32 v34, v31
	s_nop 0
	v_fma_f32 v35, -v31, v34, 1.0
	v_fmac_f32_e32 v34, v35, v34
	v_div_scale_f32 v35, vcc, 1.0, v30, 1.0
	v_mul_f32_e32 v36, v35, v34
	v_fma_f32 v37, -v31, v36, v35
	v_fmac_f32_e32 v36, v37, v34
	v_fma_f32 v31, -v31, v36, v35
	v_div_fmas_f32 v31, v31, v34, v36
	v_div_fixup_f32 v36, v31, v30, 1.0
	v_mul_f32_e32 v30, 0xbfb8aa3b, v18
	v_mul_f32_e32 v31, 0xbfb8aa3b, v19
	v_exp_f32_e32 v30, v30
	v_exp_f32_e32 v31, v31
	v_cvt_pk_bf16_f32 v29, v36, v33
	v_pk_add_f32 v[30:31], v[30:31], 1.0 op_sel_hi:[1,0]
	s_nop 0
	v_div_scale_f32 v34, s[16:17], v31, v31, 1.0
	v_rcp_f32_e32 v35, v34
	s_nop 0
	v_fma_f32 v37, -v34, v35, 1.0
	v_fmac_f32_e32 v35, v37, v35
	v_div_scale_f32 v37, vcc, 1.0, v31, 1.0
	v_mul_f32_e32 v38, v37, v35
	v_fma_f32 v39, -v34, v38, v37
	v_fmac_f32_e32 v38, v39, v35
	v_fma_f32 v34, -v34, v38, v37
	v_div_fmas_f32 v34, v34, v35, v38
	v_div_fixup_f32 v37, v34, v31, 1.0
	v_div_scale_f32 v31, s[16:17], v30, v30, 1.0
	v_rcp_f32_e32 v34, v31
	s_nop 0
	v_fma_f32 v35, -v31, v34, 1.0
	v_fmac_f32_e32 v34, v35, v34
	v_div_scale_f32 v35, vcc, 1.0, v30, 1.0
	v_mul_f32_e32 v38, v35, v34
	v_fma_f32 v39, -v31, v38, v35
	v_fmac_f32_e32 v38, v39, v34
	v_fma_f32 v31, -v31, v38, v35
	v_div_fmas_f32 v31, v31, v34, v38
	v_div_fixup_f32 v38, v31, v30, 1.0
	v_mul_f32_e32 v30, 0xbfb8aa3b, v20
	v_mul_f32_e32 v31, 0xbfb8aa3b, v21
	v_exp_f32_e32 v30, v30
	v_exp_f32_e32 v31, v31
	s_nop 0
	v_pk_add_f32 v[30:31], v[30:31], 1.0 op_sel_hi:[1,0]
	s_nop 0
	v_div_scale_f32 v34, s[16:17], v31, v31, 1.0
	v_rcp_f32_e32 v35, v34
	s_nop 0
	v_fma_f32 v39, -v34, v35, 1.0
	v_fmac_f32_e32 v35, v39, v35
	v_div_scale_f32 v39, vcc, 1.0, v31, 1.0
	v_mul_f32_e32 v40, v39, v35
	v_fma_f32 v41, -v34, v40, v39
	v_fmac_f32_e32 v40, v41, v35
	v_fma_f32 v34, -v34, v40, v39
	v_div_fmas_f32 v34, v34, v35, v40
	v_div_fixup_f32 v39, v34, v31, 1.0
	v_div_scale_f32 v31, s[16:17], v30, v30, 1.0
	v_rcp_f32_e32 v34, v31
	s_nop 0
	v_fma_f32 v35, -v31, v34, 1.0
	v_fmac_f32_e32 v34, v35, v34
	v_div_scale_f32 v35, vcc, 1.0, v30, 1.0
	v_mul_f32_e32 v40, v35, v34
	v_fma_f32 v41, -v31, v40, v35
	v_fmac_f32_e32 v40, v41, v34
	v_fma_f32 v31, -v31, v40, v35
	v_div_fmas_f32 v31, v31, v34, v40
	v_div_fixup_f32 v40, v31, v30, 1.0
	v_mul_f32_e32 v30, 0xbfb8aa3b, v22
	v_mul_f32_e32 v31, 0xbfb8aa3b, v23
	v_exp_f32_e32 v30, v30
	v_exp_f32_e32 v31, v31
	s_nop 0
	v_pk_add_f32 v[30:31], v[30:31], 1.0 op_sel_hi:[1,0]
	s_nop 0
	v_div_scale_f32 v34, s[16:17], v31, v31, 1.0
	v_rcp_f32_e32 v35, v34
	s_nop 0
	v_fma_f32 v41, -v34, v35, 1.0
	v_fmac_f32_e32 v35, v41, v35
	v_div_scale_f32 v41, vcc, 1.0, v31, 1.0
	v_mul_f32_e32 v42, v41, v35
	v_fma_f32 v43, -v34, v42, v41
	v_fmac_f32_e32 v42, v43, v35
	v_fma_f32 v34, -v34, v42, v41
	v_div_fmas_f32 v34, v34, v35, v42
	v_div_fixup_f32 v41, v34, v31, 1.0
	v_div_scale_f32 v31, s[16:17], v30, v30, 1.0
	v_rcp_f32_e32 v34, v31
	s_nop 0
	v_fma_f32 v35, -v31, v34, 1.0
	v_fmac_f32_e32 v34, v35, v34
	v_div_scale_f32 v35, vcc, 1.0, v30, 1.0
	v_mul_f32_e32 v42, v35, v34
	v_fma_f32 v43, -v31, v42, v35
	v_fmac_f32_e32 v42, v43, v34
	v_fma_f32 v31, -v31, v42, v35
	v_div_fmas_f32 v31, v31, v34, v42
	v_div_fixup_f32 v42, v31, v30, 1.0
	v_mul_f32_e32 v30, 0xbfb8aa3b, v24
	v_mul_f32_e32 v31, 0xbfb8aa3b, v25
	v_exp_f32_e32 v30, v30
	v_exp_f32_e32 v31, v31
	v_cvt_pk_bf16_f32 v32, v42, v41
	v_pk_add_f32 v[30:31], v[30:31], 1.0 op_sel_hi:[1,0]
	s_nop 0
	v_div_scale_f32 v34, s[16:17], v31, v31, 1.0
	v_rcp_f32_e32 v35, v34
	s_nop 0
	v_fma_f32 v43, -v34, v35, 1.0
	v_fmac_f32_e32 v35, v43, v35
	v_div_scale_f32 v43, vcc, 1.0, v31, 1.0
	v_mul_f32_e32 v44, v43, v35
	v_fma_f32 v45, -v34, v44, v43
	v_fmac_f32_e32 v44, v45, v35
	v_fma_f32 v34, -v34, v44, v43
	v_div_fmas_f32 v34, v34, v35, v44
	v_div_fixup_f32 v43, v34, v31, 1.0
	v_div_scale_f32 v31, s[16:17], v30, v30, 1.0
	v_rcp_f32_e32 v34, v31
	s_mov_b64 s[16:17], 0
	v_fma_f32 v35, -v31, v34, 1.0
	v_fmac_f32_e32 v34, v35, v34
	v_div_scale_f32 v35, vcc, 1.0, v30, 1.0
	v_mul_f32_e32 v44, v35, v34
	v_fma_f32 v45, -v31, v44, v35
	v_fmac_f32_e32 v44, v45, v34
	v_fma_f32 v31, -v31, v44, v35
	v_div_fmas_f32 v31, v31, v34, v44
	v_div_fixup_f32 v44, v31, v30, 1.0
	v_lshlrev_b64 v[30:31], 12, v[8:9]
	v_lshl_add_u64 v[30:31], s[40:41], 0, v[30:31]
	v_lshl_add_u64 v[34:35], v[142:143], 1, v[30:31]
	v_add_co_u32_e32 v34, vcc, 0xffffe000, v34
	v_cvt_pk_bf16_f32 v30, v38, v37
	s_nop 0
	v_addc_co_u32_e32 v35, vcc, -1, v35, vcc
	v_cvt_pk_bf16_f32 v31, v40, v39
	v_cvt_pk_bf16_f32 v33, v44, v43
	global_store_dwordx4 v[34:35], v[26:29], off offset:-3072
	global_store_dwordx4 v[34:35], v[30:33], off offset:-3056

.LBB0_319:
	s_or_b64 exec, exec, s[14:15]
	s_nop 1
	v_mov_b32_e32 v22, v220
	v_mov_b32_e32 v21, v237
	v_mov_b32_e32 v20, v236
	v_mov_b32_e32 v19, v235
	v_mov_b32_e32 v18, v234
	v_mov_b32_e32 v17, v233
	v_mov_b32_e32 v16, v232
	v_mov_b32_e32 v15, v231
	v_mov_b32_e32 v14, v230
	v_mov_b32_e32 v13, v229
	v_mov_b32_e32 v12, v228
	v_mov_b32_e32 v11, v227
	v_mov_b32_e32 v10, v226
	v_mov_b32_e32 v9, v225
	v_mov_b32_e32 v8, v224
	v_mov_b32_e32 v7, v223
	v_mov_b32_e32 v6, v222
	v_or_b32_e32 v2, 48, v2
	v_ashrrev_i32_e32 v3, 31, v2
	v_pk_mul_f32 v[4:5], v[76:77], v[22:23] op_sel_hi:[1,0]
	v_pk_mul_f32 v[24:25], v[78:79], v[22:23] op_sel_hi:[1,0]
	v_pk_mul_f32 v[26:27], v[72:73], v[22:23] op_sel_hi:[1,0]
	v_pk_mul_f32 v[28:29], v[74:75], v[22:23] op_sel_hi:[1,0]
	v_pk_mul_f32 v[30:31], v[68:69], v[22:23] op_sel_hi:[1,0]
	v_pk_mul_f32 v[32:33], v[70:71], v[22:23] op_sel_hi:[1,0]
	v_pk_mul_f32 v[34:35], v[64:65], v[22:23] op_sel_hi:[1,0]
	v_pk_mul_f32 v[22:23], v[66:67], v[22:23] op_sel_hi:[1,0]
	v_pk_mul_f32 v[4:5], v[4:5], v[6:7]
	v_pk_mul_f32 v[6:7], v[24:25], v[8:9]
	v_pk_mul_f32 v[8:9], v[26:27], v[10:11]
	v_pk_mul_f32 v[10:11], v[28:29], v[12:13]
	v_pk_mul_f32 v[12:13], v[30:31], v[14:15]
	v_pk_mul_f32 v[14:15], v[32:33], v[16:17]
	v_pk_mul_f32 v[16:17], v[34:35], v[18:19]
	v_pk_mul_f32 v[18:19], v[22:23], v[20:21]
	s_and_saveexec_b64 s[14:15], s[6:7]
	s_xor_b64 s[6:7], exec, s[14:15]
	s_cbranch_execz .LBB0_328
	s_and_b64 vcc, exec, s[8:9]
	s_mov_b64 s[8:9], -1
	s_cbranch_vccnz .LBB0_326
	s_andn2_b64 vcc, exec, s[12:13]
	s_cbranch_vccnz .LBB0_323
	v_mul_f32_e32 v0, 0xbfb8aa3b, v4
	v_mul_f32_e32 v1, 0xbfb8aa3b, v5
	v_exp_f32_e32 v0, v0
	v_exp_f32_e32 v1, v1
	v_readlane_b32 s36, v247, 2
	v_readlane_b32 s40, v247, 6
	v_readlane_b32 s41, v247, 7
	v_pk_add_f32 v[20:21], v[0:1], 1.0 op_sel_hi:[1,0]
	v_readlane_b32 s37, v247, 3
	v_div_scale_f32 v0, s[8:9], v21, v21, 1.0
	v_rcp_f32_e32 v1, v0
	v_readlane_b32 s38, v247, 4
	v_readlane_b32 s39, v247, 5
	v_readlane_b32 s42, v247, 8
	v_fma_f32 v22, -v0, v1, 1.0
	v_fmac_f32_e32 v1, v22, v1
	v_div_scale_f32 v22, vcc, 1.0, v21, 1.0
	v_mul_f32_e32 v23, v22, v1
	v_fma_f32 v24, -v0, v23, v22
	v_fmac_f32_e32 v23, v24, v1
	v_fma_f32 v0, -v0, v23, v22
	v_div_fmas_f32 v0, v0, v1, v23
	v_div_scale_f32 v1, s[8:9], v20, v20, 1.0
	v_div_fixup_f32 v0, v0, v21, 1.0
	v_rcp_f32_e32 v21, v1
	v_readlane_b32 s43, v247, 9
	v_fma_f32 v22, -v1, v21, 1.0
	v_fmac_f32_e32 v21, v22, v21
	v_div_scale_f32 v22, vcc, 1.0, v20, 1.0
	v_mul_f32_e32 v23, v22, v21
	v_fma_f32 v24, -v1, v23, v22
	v_fmac_f32_e32 v23, v24, v21
	v_fma_f32 v1, -v1, v23, v22
	v_div_fmas_f32 v1, v1, v21, v23
	v_div_fixup_f32 v1, v1, v20, 1.0
	v_mul_f32_e32 v20, 0xbfb8aa3b, v6
	v_mul_f32_e32 v21, 0xbfb8aa3b, v7
	v_exp_f32_e32 v20, v20
	v_exp_f32_e32 v21, v21
	s_nop 0
	v_pk_add_f32 v[22:23], v[20:21], 1.0 op_sel_hi:[1,0]
	s_nop 0
	v_div_scale_f32 v20, s[8:9], v23, v23, 1.0
	v_rcp_f32_e32 v21, v20
	s_nop 0
	v_fma_f32 v24, -v20, v21, 1.0
	v_fmac_f32_e32 v21, v24, v21
	v_div_scale_f32 v24, vcc, 1.0, v23, 1.0
	v_mul_f32_e32 v25, v24, v21
	v_fma_f32 v26, -v20, v25, v24
	v_fmac_f32_e32 v25, v26, v21
	v_fma_f32 v20, -v20, v25, v24
	v_div_fmas_f32 v20, v20, v21, v25
	v_div_scale_f32 v21, s[8:9], v22, v22, 1.0
	v_div_fixup_f32 v20, v20, v23, 1.0
	v_rcp_f32_e32 v23, v21
	s_nop 0
	v_fma_f32 v24, -v21, v23, 1.0
	v_fmac_f32_e32 v23, v24, v23
	v_div_scale_f32 v24, vcc, 1.0, v22, 1.0
	v_mul_f32_e32 v25, v24, v23
	v_fma_f32 v26, -v21, v25, v24
	v_fmac_f32_e32 v25, v26, v23
	v_fma_f32 v21, -v21, v25, v24
	v_div_fmas_f32 v21, v21, v23, v25
	v_div_fixup_f32 v21, v21, v22, 1.0
	v_mul_f32_e32 v22, 0xbfb8aa3b, v8
	v_mul_f32_e32 v23, 0xbfb8aa3b, v9
	v_exp_f32_e32 v22, v22
	v_exp_f32_e32 v23, v23
	s_nop 0
	v_pk_add_f32 v[22:23], v[22:23], 1.0 op_sel_hi:[1,0]
	s_nop 0
	v_div_scale_f32 v24, s[8:9], v23, v23, 1.0
	v_rcp_f32_e32 v25, v24
	s_nop 0
	v_fma_f32 v26, -v24, v25, 1.0
	v_fmac_f32_e32 v25, v26, v25
	v_div_scale_f32 v26, vcc, 1.0, v23, 1.0
	v_mul_f32_e32 v27, v26, v25
	v_fma_f32 v28, -v24, v27, v26
	v_fmac_f32_e32 v27, v28, v25
	v_fma_f32 v24, -v24, v27, v26
	v_div_fmas_f32 v24, v24, v25, v27
	v_div_fixup_f32 v24, v24, v23, 1.0
	v_div_scale_f32 v23, s[8:9], v22, v22, 1.0
	v_rcp_f32_e32 v25, v23
	s_nop 0
	v_fma_f32 v26, -v23, v25, 1.0
	v_fmac_f32_e32 v25, v26, v25
	v_div_scale_f32 v26, vcc, 1.0, v22, 1.0
	v_mul_f32_e32 v27, v26, v25
	v_fma_f32 v28, -v23, v27, v26
	v_fmac_f32_e32 v27, v28, v25
	v_fma_f32 v23, -v23, v27, v26
	v_div_fmas_f32 v23, v23, v25, v27
	v_div_fixup_f32 v25, v23, v22, 1.0
	v_mul_f32_e32 v22, 0xbfb8aa3b, v10
	v_mul_f32_e32 v23, 0xbfb8aa3b, v11
	v_exp_f32_e32 v22, v22
	v_exp_f32_e32 v23, v23
	v_cvt_pk_bf16_f32 v24, v25, v24
	v_pk_add_f32 v[22:23], v[22:23], 1.0 op_sel_hi:[1,0]
	s_nop 0
	v_div_scale_f32 v26, s[8:9], v23, v23, 1.0
	v_rcp_f32_e32 v27, v26
	s_nop 0
	v_fma_f32 v28, -v26, v27, 1.0
	v_fmac_f32_e32 v27, v28, v27
	v_div_scale_f32 v28, vcc, 1.0, v23, 1.0
	v_mul_f32_e32 v29, v28, v27
	v_fma_f32 v30, -v26, v29, v28
	v_fmac_f32_e32 v29, v30, v27
	v_fma_f32 v26, -v26, v29, v28
	v_div_fmas_f32 v26, v26, v27, v29
	v_div_fixup_f32 v26, v26, v23, 1.0
	v_div_scale_f32 v23, s[8:9], v22, v22, 1.0
	v_rcp_f32_e32 v27, v23
	s_nop 0
	v_fma_f32 v28, -v23, v27, 1.0
	v_fmac_f32_e32 v27, v28, v27
	v_div_scale_f32 v28, vcc, 1.0, v22, 1.0
	v_mul_f32_e32 v29, v28, v27
	v_fma_f32 v30, -v23, v29, v28
	v_fmac_f32_e32 v29, v30, v27
	v_fma_f32 v23, -v23, v29, v28
	v_div_fmas_f32 v23, v23, v27, v29
	v_div_fixup_f32 v27, v23, v22, 1.0
	v_mul_f32_e32 v22, 0xbfb8aa3b, v12
	v_mul_f32_e32 v23, 0xbfb8aa3b, v13
	v_exp_f32_e32 v22, v22
	v_exp_f32_e32 v23, v23
	v_cvt_pk_bf16_f32 v25, v27, v26
	v_pk_add_f32 v[22:23], v[22:23], 1.0 op_sel_hi:[1,0]
	s_nop 0
	v_div_scale_f32 v28, s[8:9], v23, v23, 1.0
	v_rcp_f32_e32 v29, v28
	s_nop 0
	v_fma_f32 v30, -v28, v29, 1.0
	v_fmac_f32_e32 v29, v30, v29
	v_div_scale_f32 v30, vcc, 1.0, v23, 1.0
	v_mul_f32_e32 v31, v30, v29
	v_fma_f32 v32, -v28, v31, v30
	v_fmac_f32_e32 v31, v32, v29
	v_fma_f32 v28, -v28, v31, v30
	v_div_fmas_f32 v28, v28, v29, v31
	v_div_fixup_f32 v28, v28, v23, 1.0
	v_div_scale_f32 v23, s[8:9], v22, v22, 1.0
	v_rcp_f32_e32 v29, v23
	s_nop 0
	v_fma_f32 v30, -v23, v29, 1.0
	v_fmac_f32_e32 v29, v30, v29
	v_div_scale_f32 v30, vcc, 1.0, v22, 1.0
	v_mul_f32_e32 v31, v30, v29
	v_fma_f32 v32, -v23, v31, v30
	v_fmac_f32_e32 v31, v32, v29
	v_fma_f32 v23, -v23, v31, v30
	v_div_fmas_f32 v23, v23, v29, v31
	v_div_fixup_f32 v29, v23, v22, 1.0
	v_mul_f32_e32 v22, 0xbfb8aa3b, v14
	v_mul_f32_e32 v23, 0xbfb8aa3b, v15
	v_exp_f32_e32 v22, v22
	v_exp_f32_e32 v23, v23
	v_cvt_pk_bf16_f32 v26, v29, v28
	v_pk_add_f32 v[22:23], v[22:23], 1.0 op_sel_hi:[1,0]
	s_nop 0
	v_div_scale_f32 v30, s[8:9], v23, v23, 1.0
	v_rcp_f32_e32 v31, v30
	s_nop 0
	v_fma_f32 v32, -v30, v31, 1.0
	v_fmac_f32_e32 v31, v32, v31
	v_div_scale_f32 v32, vcc, 1.0, v23, 1.0
	v_mul_f32_e32 v33, v32, v31
	v_fma_f32 v34, -v30, v33, v32
	v_fmac_f32_e32 v33, v34, v31
	v_fma_f32 v30, -v30, v33, v32
	v_div_fmas_f32 v30, v30, v31, v33
	v_div_fixup_f32 v32, v30, v23, 1.0
	v_div_scale_f32 v23, s[8:9], v22, v22, 1.0
	v_rcp_f32_e32 v30, v23
	s_nop 0
	v_fma_f32 v31, -v23, v30, 1.0
	v_fmac_f32_e32 v30, v31, v30
	v_div_scale_f32 v31, vcc, 1.0, v22, 1.0
	v_mul_f32_e32 v33, v31, v30
	v_fma_f32 v34, -v23, v33, v31
	v_fmac_f32_e32 v33, v34, v30
	v_fma_f32 v23, -v23, v33, v31
	v_div_fmas_f32 v23, v23, v30, v33
	v_div_fixup_f32 v33, v23, v22, 1.0
	v_mul_f32_e32 v22, 0xbfb8aa3b, v16
	v_mul_f32_e32 v23, 0xbfb8aa3b, v17
	v_exp_f32_e32 v22, v22
	v_exp_f32_e32 v23, v23
	v_cvt_pk_bf16_f32 v27, v33, v32
	v_pk_add_f32 v[22:23], v[22:23], 1.0 op_sel_hi:[1,0]
	s_nop 0
	v_div_scale_f32 v30, s[8:9], v23, v23, 1.0
	v_rcp_f32_e32 v31, v30
	s_nop 0
	v_fma_f32 v34, -v30, v31, 1.0
	v_fmac_f32_e32 v31, v34, v31
	v_div_scale_f32 v34, vcc, 1.0, v23, 1.0
	v_mul_f32_e32 v35, v34, v31
	v_fma_f32 v36, -v30, v35, v34
	v_fmac_f32_e32 v35, v36, v31
	v_fma_f32 v30, -v30, v35, v34
	v_div_fmas_f32 v30, v30, v31, v35
	v_div_fixup_f32 v34, v30, v23, 1.0
	v_div_scale_f32 v23, s[8:9], v22, v22, 1.0
	v_rcp_f32_e32 v30, v23
	s_nop 0
	v_fma_f32 v31, -v23, v30, 1.0
	v_fmac_f32_e32 v30, v31, v30
	v_div_scale_f32 v31, vcc, 1.0, v22, 1.0
	v_mul_f32_e32 v35, v31, v30
	v_fma_f32 v36, -v23, v35, v31
	v_fmac_f32_e32 v35, v36, v30
	v_fma_f32 v23, -v23, v35, v31
	v_div_fmas_f32 v23, v23, v30, v35
	v_div_fixup_f32 v35, v23, v22, 1.0
	v_mul_f32_e32 v22, 0xbfb8aa3b, v18
	v_mul_f32_e32 v23, 0xbfb8aa3b, v19
	v_exp_f32_e32 v22, v22
	v_exp_f32_e32 v23, v23
	v_cvt_pk_bf16_f32 v28, v35, v34
	v_pk_add_f32 v[22:23], v[22:23], 1.0 op_sel_hi:[1,0]
	s_nop 0
	v_div_scale_f32 v30, s[8:9], v23, v23, 1.0
	v_rcp_f32_e32 v31, v30
	s_nop 0
	v_fma_f32 v36, -v30, v31, 1.0
	v_fmac_f32_e32 v31, v36, v31
	v_div_scale_f32 v36, vcc, 1.0, v23, 1.0
	v_mul_f32_e32 v37, v36, v31
	v_fma_f32 v38, -v30, v37, v36
	v_fmac_f32_e32 v37, v38, v31
	v_fma_f32 v30, -v30, v37, v36
	v_div_fmas_f32 v30, v30, v31, v37
	v_div_fixup_f32 v36, v30, v23, 1.0
	v_div_scale_f32 v23, s[8:9], v22, v22, 1.0
	v_rcp_f32_e32 v30, v23
	s_mov_b64 s[8:9], 0
	v_fma_f32 v31, -v23, v30, 1.0
	v_fmac_f32_e32 v30, v31, v30
	v_div_scale_f32 v31, vcc, 1.0, v22, 1.0
	v_mul_f32_e32 v37, v31, v30
	v_fma_f32 v38, -v23, v37, v31
	v_fmac_f32_e32 v37, v38, v30
	v_fma_f32 v23, -v23, v37, v31
	v_div_fmas_f32 v23, v23, v30, v37
	v_div_fixup_f32 v37, v23, v22, 1.0
	v_lshlrev_b64 v[22:23], 12, v[2:3]
	v_lshl_add_u64 v[22:23], s[40:41], 0, v[22:23]
	v_lshl_add_u64 v[30:31], v[142:143], 1, v[22:23]
	v_cvt_pk_bf16_f32 v22, v1, v0
	v_add_co_u32_e32 v0, vcc, 0xffffe000, v30
	v_cvt_pk_bf16_f32 v23, v21, v20
	s_nop 0
	v_addc_co_u32_e32 v1, vcc, -1, v31, vcc
	v_cvt_pk_bf16_f32 v29, v37, v36
	global_store_dwordx4 v[0:1], v[22:25], off offset:-3072
	global_store_dwordx4 v[0:1], v[26:29], off offset:-3056
